# plain-GEMM epilogue: row-scale loads hoisted, per-section waits relaxed to vmcnt(2) pacing
# speedup vs baseline: 1.0072x; 1.0072x over previous
.LBB0_423:
	s_nop 0
	v_or_b32_e32 v116, 16, v150
	v_mad_i64_i32 v[116:117], s[8:9], v116, s22, 0
	v_lshl_add_u64 v[116:117], v[116:117], 1, s[4:5]
	v_lshl_add_u64 v[116:117], v[154:155], 1, v[116:117]
	s_waitcnt vmcnt(2)
	v_pk_mul_f32 v[114:115], v[114:115], v[210:211] op_sel_hi:[1,0]
	v_pk_mul_f32 v[112:113], v[112:113], v[210:211] op_sel_hi:[1,0]
	v_pk_mul_f32 v[118:119], v[110:111], v[210:211] op_sel_hi:[1,0]
	v_pk_mul_f32 v[110:111], v[108:109], v[210:211] op_sel_hi:[1,0]
	v_cvt_pk_bf16_f32 v108, v112, v113
	v_cvt_pk_bf16_f32 v109, v114, v115
	v_pk_mul_f32 v[106:107], v[106:107], v[210:211] op_sel_hi:[1,0]
	v_cvt_pk_bf16_f32 v110, v110, v111
	v_cvt_pk_bf16_f32 v111, v118, v119
	global_store_dwordx4 v[116:117], v[108:111], off
	v_pk_mul_f32 v[104:105], v[104:105], v[210:211] op_sel_hi:[1,0]
	s_and_b64 vcc, exec, s[42:43]
	v_pk_mul_f32 v[108:109], v[102:103], v[210:211] op_sel_hi:[1,0]
	v_pk_mul_f32 v[102:103], v[100:101], v[210:211] op_sel_hi:[1,0]
	v_cvt_pk_bf16_f32 v100, v104, v105
	v_cvt_pk_bf16_f32 v101, v106, v107
	s_nop 0
	v_cvt_pk_bf16_f32 v102, v102, v103
	v_cvt_pk_bf16_f32 v103, v108, v109
	global_store_dwordx4 v[116:117], v[100:103], off offset:256
	s_nop 1
	v_mov_b32_e32 v100, 1.0
	v_mov_b32_e32 v102, 1.0
	s_nop 0
.LBB0_425:
	v_or_b32_e32 v101, 32, v150
	v_mad_i64_i32 v[104:105], s[8:9], v101, s22, 0
	v_lshl_add_u64 v[104:105], v[104:105], 1, s[4:5]
	v_lshl_add_u64 v[104:105], v[154:155], 1, v[104:105]
	s_waitcnt vmcnt(2)
	v_pk_mul_f32 v[98:99], v[98:99], v[212:213] op_sel_hi:[1,0]
	v_pk_mul_f32 v[96:97], v[96:97], v[212:213] op_sel_hi:[1,0]
	v_pk_mul_f32 v[106:107], v[94:95], v[212:213] op_sel_hi:[1,0]
	v_pk_mul_f32 v[94:95], v[92:93], v[212:213] op_sel_hi:[1,0]
	v_cvt_pk_bf16_f32 v92, v96, v97
	v_cvt_pk_bf16_f32 v93, v98, v99
	s_and_b64 vcc, exec, s[42:43]
	v_cvt_pk_bf16_f32 v94, v94, v95
	v_cvt_pk_bf16_f32 v95, v106, v107
	global_store_dwordx4 v[104:105], v[92:95], off
	v_pk_mul_f32 v[90:91], v[90:91], v[212:213] op_sel_hi:[1,0]
	v_pk_mul_f32 v[88:89], v[88:89], v[212:213] op_sel_hi:[1,0]
	v_pk_mul_f32 v[92:93], v[86:87], v[212:213] op_sel_hi:[1,0]
	v_pk_mul_f32 v[86:87], v[84:85], v[212:213] op_sel_hi:[1,0]
	v_cvt_pk_bf16_f32 v84, v88, v89
	v_cvt_pk_bf16_f32 v85, v90, v91
	s_nop 0
	v_cvt_pk_bf16_f32 v86, v86, v87
	v_cvt_pk_bf16_f32 v87, v92, v93
	global_store_dwordx4 v[104:105], v[84:87], off offset:256
	s_nop 0
.LBB0_427:
	s_nop 0
	v_or_b32_e32 v84, 48, v150
	v_mad_i64_i32 v[84:85], s[8:9], v84, s22, 0
	v_lshl_add_u64 v[84:85], v[84:85], 1, s[4:5]
	v_lshl_add_u64 v[84:85], v[154:155], 1, v[84:85]
	s_waitcnt vmcnt(2)
	v_pk_mul_f32 v[82:83], v[82:83], v[214:215] op_sel_hi:[1,0]
	v_pk_mul_f32 v[80:81], v[80:81], v[214:215] op_sel_hi:[1,0]
	v_pk_mul_f32 v[86:87], v[78:79], v[214:215] op_sel_hi:[1,0]
	v_pk_mul_f32 v[78:79], v[76:77], v[214:215] op_sel_hi:[1,0]
	v_cvt_pk_bf16_f32 v76, v80, v81
	v_cvt_pk_bf16_f32 v77, v82, v83
	v_pk_mul_f32 v[74:75], v[74:75], v[214:215] op_sel_hi:[1,0]
	v_cvt_pk_bf16_f32 v78, v78, v79
	v_cvt_pk_bf16_f32 v79, v86, v87
	global_store_dwordx4 v[84:85], v[76:79], off
	v_pk_mul_f32 v[72:73], v[72:73], v[214:215] op_sel_hi:[1,0]
	s_and_b64 vcc, exec, s[42:43]
	v_pk_mul_f32 v[76:77], v[70:71], v[214:215] op_sel_hi:[1,0]
	v_pk_mul_f32 v[70:71], v[68:69], v[214:215] op_sel_hi:[1,0]
	v_cvt_pk_bf16_f32 v68, v72, v73
	v_cvt_pk_bf16_f32 v69, v74, v75
	s_nop 0
	v_cvt_pk_bf16_f32 v70, v70, v71
	v_cvt_pk_bf16_f32 v71, v76, v77
	global_store_dwordx4 v[84:85], v[68:71], off offset:256
	s_nop 1
	v_mov_b32_e32 v68, 1.0
	v_mov_b32_e32 v70, 1.0
	s_nop 0
.LBB0_429:
	v_add_u32_e32 v69, 0x80, v150
	v_mad_i64_i32 v[72:73], s[8:9], v69, s22, 0
	v_lshl_add_u64 v[72:73], v[72:73], 1, s[4:5]
	v_lshl_add_u64 v[72:73], v[154:155], 1, v[72:73]
	s_waitcnt vmcnt(2)
	v_pk_mul_f32 v[66:67], v[66:67], v[216:217] op_sel_hi:[1,0]
	v_pk_mul_f32 v[64:65], v[64:65], v[216:217] op_sel_hi:[1,0]
	v_pk_mul_f32 v[74:75], v[62:63], v[216:217] op_sel_hi:[1,0]
	v_pk_mul_f32 v[62:63], v[60:61], v[216:217] op_sel_hi:[1,0]
	v_cvt_pk_bf16_f32 v60, v64, v65
	v_cvt_pk_bf16_f32 v61, v66, v67
	s_and_b64 vcc, exec, s[42:43]
	v_cvt_pk_bf16_f32 v62, v62, v63
	v_cvt_pk_bf16_f32 v63, v74, v75
	global_store_dwordx4 v[72:73], v[60:63], off
	v_pk_mul_f32 v[58:59], v[58:59], v[216:217] op_sel_hi:[1,0]
	v_pk_mul_f32 v[56:57], v[56:57], v[216:217] op_sel_hi:[1,0]
	v_pk_mul_f32 v[60:61], v[54:55], v[216:217] op_sel_hi:[1,0]
	v_pk_mul_f32 v[54:55], v[52:53], v[216:217] op_sel_hi:[1,0]
	v_cvt_pk_bf16_f32 v52, v56, v57
	v_cvt_pk_bf16_f32 v53, v58, v59
	s_nop 0
	v_cvt_pk_bf16_f32 v54, v54, v55
	v_cvt_pk_bf16_f32 v55, v60, v61
	global_store_dwordx4 v[72:73], v[52:55], off offset:256
	s_nop 0
.LBB0_431:
	s_nop 0
	v_add_u32_e32 v52, 0x90, v150
	v_mad_i64_i32 v[52:53], s[8:9], v52, s22, 0
	v_lshl_add_u64 v[52:53], v[52:53], 1, s[4:5]
	v_lshl_add_u64 v[52:53], v[154:155], 1, v[52:53]
	s_waitcnt vmcnt(2)
	v_pk_mul_f32 v[50:51], v[50:51], v[218:219] op_sel_hi:[1,0]
	v_pk_mul_f32 v[48:49], v[48:49], v[218:219] op_sel_hi:[1,0]
	v_pk_mul_f32 v[54:55], v[46:47], v[218:219] op_sel_hi:[1,0]
	v_pk_mul_f32 v[46:47], v[44:45], v[218:219] op_sel_hi:[1,0]
	v_cvt_pk_bf16_f32 v44, v48, v49
	v_cvt_pk_bf16_f32 v45, v50, v51
	v_pk_mul_f32 v[42:43], v[42:43], v[218:219] op_sel_hi:[1,0]
	v_cvt_pk_bf16_f32 v46, v46, v47
	v_cvt_pk_bf16_f32 v47, v54, v55
	global_store_dwordx4 v[52:53], v[44:47], off
	v_pk_mul_f32 v[40:41], v[40:41], v[218:219] op_sel_hi:[1,0]
	s_and_b64 vcc, exec, s[42:43]
	v_pk_mul_f32 v[44:45], v[38:39], v[218:219] op_sel_hi:[1,0]
	v_pk_mul_f32 v[38:39], v[36:37], v[218:219] op_sel_hi:[1,0]
	v_cvt_pk_bf16_f32 v36, v40, v41
	v_cvt_pk_bf16_f32 v37, v42, v43
	s_nop 0
	v_cvt_pk_bf16_f32 v38, v38, v39
	v_cvt_pk_bf16_f32 v39, v44, v45
	global_store_dwordx4 v[52:53], v[36:39], off offset:256
	s_nop 1
	v_mov_b32_e32 v36, 1.0
	v_mov_b32_e32 v38, 1.0
	s_nop 0
.LBB0_433:
	v_add_u32_e32 v37, 0xa0, v150
	v_mad_i64_i32 v[40:41], s[8:9], v37, s22, 0
	v_lshl_add_u64 v[40:41], v[40:41], 1, s[4:5]
	v_lshl_add_u64 v[40:41], v[154:155], 1, v[40:41]
	s_waitcnt vmcnt(2)
	v_pk_mul_f32 v[34:35], v[34:35], v[220:221] op_sel_hi:[1,0]
	v_pk_mul_f32 v[32:33], v[32:33], v[220:221] op_sel_hi:[1,0]
	v_pk_mul_f32 v[42:43], v[30:31], v[220:221] op_sel_hi:[1,0]
	v_pk_mul_f32 v[30:31], v[28:29], v[220:221] op_sel_hi:[1,0]
	v_cvt_pk_bf16_f32 v28, v32, v33
	v_cvt_pk_bf16_f32 v29, v34, v35
	s_and_b64 vcc, exec, s[42:43]
	v_cvt_pk_bf16_f32 v30, v30, v31
	v_cvt_pk_bf16_f32 v31, v42, v43
	global_store_dwordx4 v[40:41], v[28:31], off
	v_pk_mul_f32 v[26:27], v[26:27], v[220:221] op_sel_hi:[1,0]
	v_pk_mul_f32 v[24:25], v[24:25], v[220:221] op_sel_hi:[1,0]
	v_pk_mul_f32 v[28:29], v[22:23], v[220:221] op_sel_hi:[1,0]
	v_pk_mul_f32 v[22:23], v[20:21], v[220:221] op_sel_hi:[1,0]
	v_cvt_pk_bf16_f32 v20, v24, v25
	v_cvt_pk_bf16_f32 v21, v26, v27
	s_nop 0
	v_cvt_pk_bf16_f32 v22, v22, v23
	v_cvt_pk_bf16_f32 v23, v28, v29
	global_store_dwordx4 v[40:41], v[20:23], off offset:256
	s_nop 0
.LBB0_435:
	s_nop 0
	v_add_u32_e32 v20, 0xb0, v150
	v_mad_i64_i32 v[20:21], s[8:9], v20, s22, 0
	v_lshl_add_u64 v[20:21], v[20:21], 1, s[4:5]
	v_lshl_add_u64 v[20:21], v[154:155], 1, v[20:21]
	s_waitcnt vmcnt(2)
	v_pk_mul_f32 v[18:19], v[18:19], v[222:223] op_sel_hi:[1,0]
	v_pk_mul_f32 v[16:17], v[16:17], v[222:223] op_sel_hi:[1,0]
	v_pk_mul_f32 v[22:23], v[14:15], v[222:223] op_sel_hi:[1,0]
	v_pk_mul_f32 v[14:15], v[12:13], v[222:223] op_sel_hi:[1,0]
	v_cvt_pk_bf16_f32 v12, v16, v17
	v_cvt_pk_bf16_f32 v13, v18, v19
	s_and_b64 vcc, exec, s[40:41]
	v_cvt_pk_bf16_f32 v14, v14, v15
	v_cvt_pk_bf16_f32 v15, v22, v23
	global_store_dwordx4 v[20:21], v[12:15], off
	s_mov_b64 s[40:41], -1
	v_pk_mul_f32 v[10:11], v[10:11], v[222:223] op_sel_hi:[1,0]
	v_pk_mul_f32 v[12:13], v[6:7], v[222:223] op_sel_hi:[1,0]
	v_pk_mul_f32 v[6:7], v[4:5], v[222:223] op_sel_hi:[1,0]
	v_pk_mul_f32 v[8:9], v[8:9], v[222:223] op_sel_hi:[1,0]
	s_nop 0
	v_cvt_pk_bf16_f32 v4, v8, v9
	v_cvt_pk_bf16_f32 v5, v10, v11
	v_cvt_pk_bf16_f32 v6, v6, v7
	v_cvt_pk_bf16_f32 v7, v12, v13
	global_store_dwordx4 v[20:21], v[4:7], off offset:256
	s_cbranch_vccnz .LBB0_408
	s_and_b64 vcc, exec, s[38:39]
	s_cbranch_vccnz .LBB0_407
	s_barrier
	s_branch .LBB0_407
